# accumulator zeroing with v_mov_b64 (64 instead of 128 VALU per tile) and no store-drain vmcnt(0) before the next tile's K-loop in P5/P9/P10
# baseline (speedup 1.0000x reference)
.LBB0_305:
	s_ashr_i32 s21, s20, 31
	s_lshl_b64 s[22:23], s[20:21], 20
	s_add_u32 s22, s52, s22
	s_addc_u32 s23, s53, s23
	s_and_b64 s[24:25], s[0:1], exec
	s_cselect_b32 s3, s23, s29
	s_cselect_b32 s21, s22, s28
	s_ashr_i32 s19, s18, 31
	s_lshl_b64 s[24:25], s[18:19], 20
	s_add_u32 s24, s12, s24
	s_addc_u32 s25, s13, s25
	s_and_b64 s[34:35], s[0:1], exec
	s_cselect_b32 s19, s25, s31
	s_cselect_b32 s27, s24, s30
	s_add_u32 s28, s28, 0x80080
	s_addc_u32 s29, s29, 0
	s_add_u32 s48, s30, 0x100
	v_mov_b64_e32 v[2:3], 0
	s_addc_u32 s49, s31, 0
	s_mov_b32 s50, -2
	v_mov_b64_e32 v[4:5], 0
	v_mov_b64_e32 v[6:7], 0
	v_mov_b64_e32 v[8:9], 0
	v_mov_b64_e32 v[18:19], 0
	v_mov_b64_e32 v[20:21], 0
	v_mov_b64_e32 v[22:23], 0
	v_mov_b64_e32 v[24:25], 0
	v_mov_b64_e32 v[34:35], 0
	v_mov_b64_e32 v[36:37], 0
	v_mov_b64_e32 v[38:39], 0
	v_mov_b64_e32 v[40:41], 0
	v_mov_b64_e32 v[50:51], 0
	v_mov_b64_e32 v[52:53], 0
	v_mov_b64_e32 v[54:55], 0
	v_mov_b64_e32 v[56:57], 0
	v_mov_b64_e32 v[10:11], 0
	v_mov_b64_e32 v[12:13], 0
	v_mov_b64_e32 v[14:15], 0
	v_mov_b64_e32 v[16:17], 0
	v_mov_b64_e32 v[26:27], 0
	v_mov_b64_e32 v[28:29], 0
	v_mov_b64_e32 v[30:31], 0
	v_mov_b64_e32 v[32:33], 0
	v_mov_b64_e32 v[42:43], 0
	v_mov_b64_e32 v[44:45], 0
	v_mov_b64_e32 v[46:47], 0
	v_mov_b64_e32 v[48:49], 0
	v_mov_b64_e32 v[58:59], 0
	v_mov_b64_e32 v[60:61], 0
	v_mov_b64_e32 v[62:63], 0
	v_mov_b64_e32 v[64:65], 0
	v_mov_b64_e32 v[66:67], 0
	v_mov_b64_e32 v[68:69], 0
	v_mov_b64_e32 v[70:71], 0
	v_mov_b64_e32 v[72:73], 0
	v_mov_b64_e32 v[82:83], 0
	v_mov_b64_e32 v[84:85], 0
	v_mov_b64_e32 v[86:87], 0
	v_mov_b64_e32 v[88:89], 0
	v_mov_b64_e32 v[98:99], 0
	v_mov_b64_e32 v[100:101], 0
	v_mov_b64_e32 v[102:103], 0
	v_mov_b64_e32 v[104:105], 0
	v_mov_b64_e32 v[114:115], 0
	v_mov_b64_e32 v[116:117], 0
	v_mov_b64_e32 v[118:119], 0
	v_mov_b64_e32 v[120:121], 0
	v_mov_b64_e32 v[74:75], 0
	v_mov_b64_e32 v[76:77], 0
	v_mov_b64_e32 v[78:79], 0
	v_mov_b64_e32 v[80:81], 0
	v_mov_b64_e32 v[90:91], 0
	v_mov_b64_e32 v[92:93], 0
	v_mov_b64_e32 v[94:95], 0
	v_mov_b64_e32 v[96:97], 0
	v_mov_b64_e32 v[106:107], 0
	v_mov_b64_e32 v[108:109], 0
	v_mov_b64_e32 v[110:111], 0
	v_mov_b64_e32 v[112:113], 0
	v_mov_b64_e32 v[122:123], 0
	v_mov_b64_e32 v[124:125], 0
	v_mov_b64_e32 v[126:127], 0
	v_mov_b64_e32 v[128:129], 0

.LBB0_985:
	s_ashr_i32 s17, s16, 31
	s_lshl_b64 s[18:19], s[16:17], 19
	s_add_u32 s18, s52, s18
	s_addc_u32 s19, s53, s19
	s_and_b64 s[20:21], s[0:1], exec
	s_cselect_b32 s17, s19, s25
	s_cselect_b32 s45, s18, s24
	s_ashr_i32 s15, s14, 31
	s_lshl_b64 s[20:21], s[14:15], 19
	s_add_u32 s20, s58, s20
	s_addc_u32 s21, s59, s21
	s_and_b64 s[28:29], s[0:1], exec
	s_cselect_b32 s15, s21, s27
	s_cselect_b32 s46, s20, s26
	s_add_u32 s24, s24, 0x40080
	s_addc_u32 s25, s25, 0
	s_add_u32 s47, s26, 0x100
	v_mov_b64_e32 v[2:3], 0
	s_addc_u32 s48, s27, 0
	s_mov_b32 s49, -2
	v_mov_b64_e32 v[4:5], 0
	v_mov_b64_e32 v[6:7], 0
	v_mov_b64_e32 v[8:9], 0
	v_mov_b64_e32 v[18:19], 0
	v_mov_b64_e32 v[20:21], 0
	v_mov_b64_e32 v[22:23], 0
	v_mov_b64_e32 v[24:25], 0
	v_mov_b64_e32 v[34:35], 0
	v_mov_b64_e32 v[36:37], 0
	v_mov_b64_e32 v[38:39], 0
	v_mov_b64_e32 v[40:41], 0
	v_mov_b64_e32 v[50:51], 0
	v_mov_b64_e32 v[52:53], 0
	v_mov_b64_e32 v[54:55], 0
	v_mov_b64_e32 v[56:57], 0
	v_mov_b64_e32 v[10:11], 0
	v_mov_b64_e32 v[12:13], 0
	v_mov_b64_e32 v[14:15], 0
	v_mov_b64_e32 v[16:17], 0
	v_mov_b64_e32 v[26:27], 0
	v_mov_b64_e32 v[28:29], 0
	v_mov_b64_e32 v[30:31], 0
	v_mov_b64_e32 v[32:33], 0
	v_mov_b64_e32 v[42:43], 0
	v_mov_b64_e32 v[44:45], 0
	v_mov_b64_e32 v[46:47], 0
	v_mov_b64_e32 v[48:49], 0
	v_mov_b64_e32 v[58:59], 0
	v_mov_b64_e32 v[60:61], 0
	v_mov_b64_e32 v[62:63], 0
	v_mov_b64_e32 v[64:65], 0
	v_mov_b64_e32 v[66:67], 0
	v_mov_b64_e32 v[68:69], 0
	v_mov_b64_e32 v[70:71], 0
	v_mov_b64_e32 v[72:73], 0
	v_mov_b64_e32 v[82:83], 0
	v_mov_b64_e32 v[84:85], 0
	v_mov_b64_e32 v[86:87], 0
	v_mov_b64_e32 v[88:89], 0
	v_mov_b64_e32 v[98:99], 0
	v_mov_b64_e32 v[100:101], 0
	v_mov_b64_e32 v[102:103], 0
	v_mov_b64_e32 v[104:105], 0
	v_mov_b64_e32 v[114:115], 0
	v_mov_b64_e32 v[116:117], 0
	v_mov_b64_e32 v[118:119], 0
	v_mov_b64_e32 v[120:121], 0
	v_mov_b64_e32 v[74:75], 0
	v_mov_b64_e32 v[76:77], 0
	v_mov_b64_e32 v[78:79], 0
	v_mov_b64_e32 v[80:81], 0
	v_mov_b64_e32 v[90:91], 0
	v_mov_b64_e32 v[92:93], 0
	v_mov_b64_e32 v[94:95], 0
	v_mov_b64_e32 v[96:97], 0
	v_mov_b64_e32 v[106:107], 0
	v_mov_b64_e32 v[108:109], 0
	v_mov_b64_e32 v[110:111], 0
	v_mov_b64_e32 v[112:113], 0
	v_mov_b64_e32 v[122:123], 0
	v_mov_b64_e32 v[124:125], 0
	v_mov_b64_e32 v[126:127], 0
	v_mov_b64_e32 v[128:129], 0

.LBB0_1053:
	s_ashr_i32 s17, s16, 31
	s_lshl_b64 s[18:19], s[16:17], 19
	s_add_u32 s18, s70, s18
	s_addc_u32 s19, s58, s19
	s_and_b64 s[20:21], s[4:5], exec
	s_cselect_b32 s17, s19, s25
	s_cselect_b32 s46, s18, s24
	s_ashr_i32 s15, s14, 31
	s_lshl_b64 s[20:21], s[14:15], 19
	s_add_u32 s20, s68, s20
	s_addc_u32 s21, s69, s21
	s_and_b64 s[28:29], s[4:5], exec
	s_cselect_b32 s15, s21, s27
	s_cselect_b32 s47, s20, s26
	s_add_u32 s24, s24, 0x40080
	s_addc_u32 s25, s25, 0
	s_add_u32 s48, s26, 0x100
	v_mov_b64_e32 v[10:11], 0
	s_addc_u32 s49, s27, 0
	s_mov_b32 s50, -2
	v_mov_b64_e32 v[12:13], 0
	v_mov_b64_e32 v[14:15], 0
	v_mov_b64_e32 v[16:17], 0
	v_mov_b64_e32 v[26:27], 0
	v_mov_b64_e32 v[28:29], 0
	v_mov_b64_e32 v[30:31], 0
	v_mov_b64_e32 v[32:33], 0
	v_mov_b64_e32 v[42:43], 0
	v_mov_b64_e32 v[44:45], 0
	v_mov_b64_e32 v[46:47], 0
	v_mov_b64_e32 v[48:49], 0
	v_mov_b64_e32 v[58:59], 0
	v_mov_b64_e32 v[60:61], 0
	v_mov_b64_e32 v[62:63], 0
	v_mov_b64_e32 v[64:65], 0
	v_mov_b64_e32 v[2:3], 0
	v_mov_b64_e32 v[4:5], 0
	v_mov_b64_e32 v[6:7], 0
	v_mov_b64_e32 v[8:9], 0
	s_waitcnt vmcnt(0)
	v_mov_b64_e32 v[18:19], 0
	v_mov_b64_e32 v[20:21], 0
	v_mov_b64_e32 v[22:23], 0
	v_mov_b64_e32 v[24:25], 0
	v_mov_b64_e32 v[34:35], 0
	v_mov_b64_e32 v[36:37], 0
	v_mov_b64_e32 v[38:39], 0
	v_mov_b64_e32 v[40:41], 0
	v_mov_b64_e32 v[50:51], 0
	v_mov_b64_e32 v[52:53], 0
	v_mov_b64_e32 v[54:55], 0
	v_mov_b64_e32 v[56:57], 0
	v_mov_b64_e32 v[74:75], 0
	v_mov_b64_e32 v[76:77], 0
	v_mov_b64_e32 v[78:79], 0
	v_mov_b64_e32 v[80:81], 0
	v_mov_b64_e32 v[90:91], 0
	v_mov_b64_e32 v[92:93], 0
	v_mov_b64_e32 v[94:95], 0
	v_mov_b64_e32 v[96:97], 0
	v_mov_b64_e32 v[106:107], 0
	v_mov_b64_e32 v[108:109], 0
	v_mov_b64_e32 v[110:111], 0
	v_mov_b64_e32 v[112:113], 0
	v_mov_b64_e32 v[122:123], 0
	v_mov_b64_e32 v[124:125], 0
	v_mov_b64_e32 v[126:127], 0
	v_mov_b64_e32 v[128:129], 0
	v_mov_b64_e32 v[66:67], 0
	v_mov_b64_e32 v[68:69], 0
	v_mov_b64_e32 v[70:71], 0
	v_mov_b64_e32 v[72:73], 0
	v_mov_b64_e32 v[82:83], 0
	v_mov_b64_e32 v[84:85], 0
	v_mov_b64_e32 v[86:87], 0
	v_mov_b64_e32 v[88:89], 0
	v_mov_b64_e32 v[98:99], 0
	v_mov_b64_e32 v[100:101], 0
	v_mov_b64_e32 v[102:103], 0
	v_mov_b64_e32 v[104:105], 0
	v_mov_b64_e32 v[114:115], 0
	v_mov_b64_e32 v[116:117], 0
	v_mov_b64_e32 v[118:119], 0
	v_mov_b64_e32 v[120:121], 0

.LBB0_1123:
	s_ashr_i32 s21, s20, 31
	s_lshl_b64 s[22:23], s[20:21], 20
	s_add_u32 s22, s54, s22
	s_addc_u32 s23, s55, s23
	s_and_b64 s[24:25], s[8:9], exec
	s_cselect_b32 s21, s23, s31
	s_cselect_b32 s27, s22, s30
	s_ashr_i32 s19, s18, 31
	s_lshl_b64 s[24:25], s[18:19], 20
	v_readlane_b32 s36, v241, 44
	v_readlane_b32 s37, v241, 45
	s_add_u32 s24, s36, s24
	s_addc_u32 s25, s37, s25
	s_and_b64 s[36:37], s[8:9], exec
	s_cselect_b32 s19, s25, s35
	s_cselect_b32 s29, s24, s34
	s_add_u32 s30, s30, 0x80080
	s_addc_u32 s31, s31, 0
	s_add_u32 s57, s34, 0x100
	v_mov_b64_e32 v[2:3], 0
	s_addc_u32 s58, s35, 0
	s_mov_b32 s59, -2
	s_waitcnt lgkmcnt(0)
	v_mov_b64_e32 v[4:5], 0
	v_mov_b64_e32 v[6:7], 0
	v_mov_b64_e32 v[8:9], 0
	s_waitcnt vmcnt(0)
	v_mov_b64_e32 v[18:19], 0
	v_mov_b64_e32 v[20:21], 0
	v_mov_b64_e32 v[22:23], 0
	v_mov_b64_e32 v[24:25], 0
	v_mov_b64_e32 v[34:35], 0
	v_mov_b64_e32 v[36:37], 0
	v_mov_b64_e32 v[38:39], 0
	v_mov_b64_e32 v[40:41], 0
	v_mov_b64_e32 v[50:51], 0
	v_mov_b64_e32 v[52:53], 0
	v_mov_b64_e32 v[54:55], 0
	v_mov_b64_e32 v[56:57], 0
	v_mov_b64_e32 v[10:11], 0
	v_mov_b64_e32 v[12:13], 0
	v_mov_b64_e32 v[14:15], 0
	v_mov_b64_e32 v[16:17], 0
	v_mov_b64_e32 v[26:27], 0
	v_mov_b64_e32 v[28:29], 0
	v_mov_b64_e32 v[30:31], 0
	v_mov_b64_e32 v[32:33], 0
	v_mov_b64_e32 v[42:43], 0
	v_mov_b64_e32 v[44:45], 0
	v_mov_b64_e32 v[46:47], 0
	v_mov_b64_e32 v[48:49], 0
	v_mov_b64_e32 v[58:59], 0
	v_mov_b64_e32 v[60:61], 0
	v_mov_b64_e32 v[62:63], 0
	v_mov_b64_e32 v[64:65], 0
	v_mov_b64_e32 v[66:67], 0
	v_mov_b64_e32 v[68:69], 0
	v_mov_b64_e32 v[70:71], 0
	v_mov_b64_e32 v[72:73], 0
	v_mov_b64_e32 v[82:83], 0
	v_mov_b64_e32 v[84:85], 0
	v_mov_b64_e32 v[94:95], 0
	v_mov_b64_e32 v[96:97], 0
	v_mov_b64_e32 v[114:115], 0
	v_mov_b64_e32 v[116:117], 0
	v_mov_b64_e32 v[118:119], 0
	v_mov_b64_e32 v[120:121], 0
	v_mov_b64_e32 v[130:131], 0
	v_mov_b64_e32 v[132:133], 0
	v_mov_b64_e32 v[134:135], 0
	v_mov_b64_e32 v[136:137], 0
	v_mov_b64_e32 v[74:75], 0
	v_mov_b64_e32 v[76:77], 0
	v_mov_b64_e32 v[78:79], 0
	v_mov_b64_e32 v[80:81], 0
	v_mov_b64_e32 v[106:107], 0
	v_mov_b64_e32 v[108:109], 0
	v_mov_b64_e32 v[110:111], 0
	v_mov_b64_e32 v[112:113], 0
	v_mov_b64_e32 v[122:123], 0
	v_mov_b64_e32 v[124:125], 0
	v_mov_b64_e32 v[126:127], 0
	v_mov_b64_e32 v[128:129], 0
	v_mov_b64_e32 v[138:139], 0
	v_mov_b64_e32 v[140:141], 0
	v_mov_b64_e32 v[142:143], 0
	v_mov_b64_e32 v[144:145], 0

.LBB0_1207:
	s_ashr_i32 s21, s20, 31
	s_lshl_b64 s[22:23], s[20:21], 20
	s_add_u32 s22, s52, s22
	s_addc_u32 s23, s53, s23
	s_and_b64 s[24:25], s[0:1], exec
	s_cselect_b32 s21, s23, s27
	s_cselect_b32 s50, s22, s26
	s_ashr_i32 s19, s18, 31
	s_lshl_b64 s[24:25], s[18:19], 20
	v_readlane_b32 s30, v240, 23
	v_readlane_b32 s31, v240, 24
	s_add_u32 s24, s30, s24
	s_addc_u32 s25, s31, s25
	s_and_b64 s[30:31], s[0:1], exec
	s_cselect_b32 s19, s25, s29
	s_cselect_b32 s51, s24, s28
	s_add_u32 s26, s26, 0x80080
	s_addc_u32 s27, s27, 0
	s_add_u32 s56, s28, 0x100
	v_mov_b64_e32 v[2:3], 0
	s_addc_u32 s57, s29, 0
	s_mov_b32 s58, -2
	v_mov_b64_e32 v[4:5], 0
	v_mov_b64_e32 v[6:7], 0
	v_mov_b64_e32 v[8:9], 0
	v_mov_b64_e32 v[18:19], 0
	v_mov_b64_e32 v[20:21], 0
	v_mov_b64_e32 v[22:23], 0
	v_mov_b64_e32 v[24:25], 0
	v_mov_b64_e32 v[34:35], 0
	v_mov_b64_e32 v[36:37], 0
	v_mov_b64_e32 v[38:39], 0
	v_mov_b64_e32 v[40:41], 0
	v_mov_b64_e32 v[50:51], 0
	v_mov_b64_e32 v[52:53], 0
	v_mov_b64_e32 v[54:55], 0
	v_mov_b64_e32 v[56:57], 0
	v_mov_b64_e32 v[10:11], 0
	v_mov_b64_e32 v[12:13], 0
	v_mov_b64_e32 v[14:15], 0
	v_mov_b64_e32 v[16:17], 0
	v_mov_b64_e32 v[26:27], 0
	v_mov_b64_e32 v[28:29], 0
	v_mov_b64_e32 v[30:31], 0
	v_mov_b64_e32 v[32:33], 0
	v_mov_b64_e32 v[42:43], 0
	v_mov_b64_e32 v[44:45], 0
	v_mov_b64_e32 v[46:47], 0
	v_mov_b64_e32 v[48:49], 0
	v_mov_b64_e32 v[58:59], 0
	v_mov_b64_e32 v[60:61], 0
	v_mov_b64_e32 v[62:63], 0
	v_mov_b64_e32 v[64:65], 0
	v_mov_b64_e32 v[66:67], 0
	v_mov_b64_e32 v[68:69], 0
	v_mov_b64_e32 v[70:71], 0
	v_mov_b64_e32 v[72:73], 0
	v_mov_b64_e32 v[82:83], 0
	v_mov_b64_e32 v[84:85], 0
	v_mov_b64_e32 v[86:87], 0
	v_mov_b64_e32 v[88:89], 0
	v_mov_b64_e32 v[114:115], 0
	v_mov_b64_e32 v[116:117], 0
	v_mov_b64_e32 v[118:119], 0
	v_mov_b64_e32 v[120:121], 0
	v_mov_b64_e32 v[130:131], 0
	v_mov_b64_e32 v[132:133], 0
	v_mov_b64_e32 v[134:135], 0
	v_mov_b64_e32 v[136:137], 0
	v_mov_b64_e32 v[74:75], 0
	v_mov_b64_e32 v[76:77], 0
	v_mov_b64_e32 v[78:79], 0
	v_mov_b64_e32 v[80:81], 0
	v_mov_b64_e32 v[90:91], 0
	v_mov_b64_e32 v[92:93], 0
	v_mov_b64_e32 v[94:95], 0
	v_mov_b64_e32 v[96:97], 0
	v_mov_b64_e32 v[122:123], 0
	v_mov_b64_e32 v[124:125], 0
	v_mov_b64_e32 v[126:127], 0
	v_mov_b64_e32 v[128:129], 0
	v_mov_b64_e32 v[138:139], 0
	v_mov_b64_e32 v[140:141], 0
	v_mov_b64_e32 v[142:143], 0
	v_mov_b64_e32 v[144:145], 0

.LBB0_1283:
	s_add_u32 s58, s28, 0x100
	v_mov_b64_e32 v[2:3], 0
	s_addc_u32 s59, s29, 0
	s_mov_b32 s60, -2
	v_mov_b64_e32 v[4:5], 0
	v_mov_b64_e32 v[6:7], 0
	v_mov_b64_e32 v[8:9], 0
	v_mov_b64_e32 v[18:19], 0
	v_mov_b64_e32 v[20:21], 0
	v_mov_b64_e32 v[22:23], 0
	v_mov_b64_e32 v[24:25], 0
	v_mov_b64_e32 v[34:35], 0
	v_mov_b64_e32 v[36:37], 0
	v_mov_b64_e32 v[38:39], 0
	v_mov_b64_e32 v[40:41], 0
	v_mov_b64_e32 v[50:51], 0
	v_mov_b64_e32 v[52:53], 0
	v_mov_b64_e32 v[54:55], 0
	v_mov_b64_e32 v[56:57], 0
	v_mov_b64_e32 v[10:11], 0
	v_mov_b64_e32 v[12:13], 0
	v_mov_b64_e32 v[14:15], 0
	v_mov_b64_e32 v[16:17], 0
	v_mov_b64_e32 v[26:27], 0
	v_mov_b64_e32 v[28:29], 0
	v_mov_b64_e32 v[30:31], 0
	v_mov_b64_e32 v[32:33], 0
	v_mov_b64_e32 v[42:43], 0
	v_mov_b64_e32 v[44:45], 0
	v_mov_b64_e32 v[46:47], 0
	v_mov_b64_e32 v[48:49], 0
	v_mov_b64_e32 v[58:59], 0
	v_mov_b64_e32 v[60:61], 0
	v_mov_b64_e32 v[62:63], 0
	v_mov_b64_e32 v[64:65], 0
	v_mov_b64_e32 v[66:67], 0
	v_mov_b64_e32 v[68:69], 0
	v_mov_b64_e32 v[70:71], 0
	v_mov_b64_e32 v[72:73], 0
	v_mov_b64_e32 v[82:83], 0
	v_mov_b64_e32 v[84:85], 0
	v_mov_b64_e32 v[86:87], 0
	v_mov_b64_e32 v[88:89], 0
	v_mov_b64_e32 v[98:99], 0
	v_mov_b64_e32 v[100:101], 0
	v_mov_b64_e32 v[102:103], 0
	v_mov_b64_e32 v[104:105], 0
	v_mov_b64_e32 v[114:115], 0
	v_mov_b64_e32 v[116:117], 0
	v_mov_b64_e32 v[118:119], 0
	v_mov_b64_e32 v[120:121], 0
	v_mov_b64_e32 v[74:75], 0
	v_mov_b64_e32 v[76:77], 0
	v_mov_b64_e32 v[78:79], 0
	v_mov_b64_e32 v[80:81], 0
	v_mov_b64_e32 v[90:91], 0
	v_mov_b64_e32 v[92:93], 0
	v_mov_b64_e32 v[94:95], 0
	v_mov_b64_e32 v[96:97], 0
	v_mov_b64_e32 v[106:107], 0
	v_mov_b64_e32 v[108:109], 0
	v_mov_b64_e32 v[110:111], 0
	v_mov_b64_e32 v[112:113], 0
	v_mov_b64_e32 v[138:139], 0
	v_mov_b64_e32 v[140:141], 0
	v_mov_b64_e32 v[142:143], 0
	v_mov_b64_e32 v[144:145], 0
